# best cache-policy version + layer-0 p conversion relocated into the out-proj slot with nt loads
# speedup vs baseline: 1.0252x; 1.0252x over previous
; __device__ __forceinline__ unsigned cvt_pk(float lo, float hi) { unsigned r; asm("v_cvt_pk_bf16_f32 %0, %1, %2" : "=v"(r) : "v"(lo), "v"(hi)); return r; }
; __device__ __forceinline__ void convert_flat(const float* src, bf16* dst, size_t n, size_t gtid, size_t gthreads) {
;     for (size_t i = gtid * 8; i < n; i += gthreads * 8) {
;         const f32x4 a = *(const f32x4*)(src + i), b = *(const f32x4*)(src + i + 4);
;         v4u w; w.x = cvt_pk(a[0], a[1]); w.y = cvt_pk(a[2], a[3]); w.z = cvt_pk(b[0], b[1]); w.w = cvt_pk(b[2], b[3]);
;         *(v4u*)(dst + i) = w;
;     }
; }
;     bf16* PB = (bf16*)(ws + WS_PB);
;     if (part & 1) {
;     convert_flat(I.p_p + (size_t)l * MP * DPLE, PB + (size_t)l * MT * DPLE, (size_t)MP * DPLE, gtid, gth);
;     convert_flat(I.p_s + (size_t)l * MS * DPLE, PB + (size_t)l * MT * DPLE + (size_t)MP * DPLE, (size_t)MS * DPLE, gtid, gth);
;     }
.Lcvp_p3:
	s_cmp_lg_u32 s64, 0x100
	s_cbranch_scc1 .LBB0_571
	v_readlane_b32 s9, v249, 46
	v_readlane_b32 s10, v249, 0
	v_readlane_b32 s0, v249, 1
	v_readlane_b32 s1, v249, 2
	v_readlane_b32 s2, v250, 0
	v_readlane_b32 s3, v250, 1
	v_readlane_b32 s12, v250, 2
	v_readlane_b32 s13, v250, 3
	v_mbcnt_lo_u32_b32 v32, -1, 0
	v_mbcnt_hi_u32_b32 v32, -1, v32
	s_nop 3
	s_add_i32 s9, s9, -16
	s_lshl_b32 s9, s9, 3
	s_add_i32 s10, s9, s10
	s_lshl_b32 s9, s10, 6
	v_add_u32_e32 v32, s9, v32
	v_lshlrev_b32_e32 v33, 5, v32
	v_lshlrev_b32_e32 v34, 4, v32
	s_add_u32 s6, s0, 0x19080000
	s_addc_u32 s7, s1, 0
	s_cmp_lt_u32 s10, 0x200
	s_cbranch_scc0 .Lcvp_a
	global_load_dwordx4 v[108:111], v33, s[12:13] nt
	global_load_dwordx4 v[112:115], v33, s[12:13] offset:16 nt
.Lcvp_a:
	s_cmp_lt_u32 s10, 0x400
	s_cbranch_scc0 .Lcvp_b
	s_add_u32 s54, s2, 0x1e00000
	s_addc_u32 s55, s3, 0
	global_load_dwordx4 v[100:103], v33, s[54:55] nt
	global_load_dwordx4 v[104:107], v33, s[54:55] offset:16 nt
.Lcvp_b:
	global_load_dwordx4 v[36:39], v33, s[2:3] nt
	global_load_dwordx4 v[40:43], v33, s[2:3] offset:16 nt
	s_add_u32 s2, s2, 0x3c0000
	s_addc_u32 s3, s3, 0
	global_load_dwordx4 v[44:47], v33, s[2:3] nt
	global_load_dwordx4 v[48:51], v33, s[2:3] offset:16 nt
	s_add_u32 s2, s2, 0x3c0000
	s_addc_u32 s3, s3, 0
	global_load_dwordx4 v[52:55], v33, s[2:3] nt
	global_load_dwordx4 v[56:59], v33, s[2:3] offset:16 nt
	s_add_u32 s2, s2, 0x3c0000
	s_addc_u32 s3, s3, 0
	global_load_dwordx4 v[60:63], v33, s[2:3] nt
	global_load_dwordx4 v[64:67], v33, s[2:3] offset:16 nt
	s_add_u32 s2, s2, 0x3c0000
	s_addc_u32 s3, s3, 0
	global_load_dwordx4 v[68:71], v33, s[2:3] nt
	global_load_dwordx4 v[72:75], v33, s[2:3] offset:16 nt
	s_add_u32 s2, s2, 0x3c0000
	s_addc_u32 s3, s3, 0
	global_load_dwordx4 v[76:79], v33, s[2:3] nt
	global_load_dwordx4 v[80:83], v33, s[2:3] offset:16 nt
	s_add_u32 s2, s2, 0x3c0000
	s_addc_u32 s3, s3, 0
	global_load_dwordx4 v[84:87], v33, s[2:3] nt
	global_load_dwordx4 v[88:91], v33, s[2:3] offset:16 nt
	s_add_u32 s2, s2, 0x3c0000
	s_addc_u32 s3, s3, 0
	global_load_dwordx4 v[92:95], v33, s[2:3] nt
	global_load_dwordx4 v[96:99], v33, s[2:3] offset:16 nt
	s_add_u32 s2, s2, 0x3c0000
	s_addc_u32 s3, s3, 0
	s_waitcnt vmcnt(14)
	v_cvt_pk_bf16_f32 v36, v36, v37
	v_cvt_pk_bf16_f32 v37, v38, v39
	v_cvt_pk_bf16_f32 v38, v40, v41
	v_cvt_pk_bf16_f32 v39, v42, v43
	global_store_dwordx4 v34, v[36:39], s[6:7]
	s_add_u32 s6, s6, 0x1e0000
	s_addc_u32 s7, s7, 0
	s_waitcnt vmcnt(13)
	v_cvt_pk_bf16_f32 v44, v44, v45
	v_cvt_pk_bf16_f32 v45, v46, v47
	v_cvt_pk_bf16_f32 v46, v48, v49
	v_cvt_pk_bf16_f32 v47, v50, v51
	global_store_dwordx4 v34, v[44:47], s[6:7]
	s_add_u32 s6, s6, 0x1e0000
	s_addc_u32 s7, s7, 0
	s_waitcnt vmcnt(12)
	v_cvt_pk_bf16_f32 v52, v52, v53
	v_cvt_pk_bf16_f32 v53, v54, v55
	v_cvt_pk_bf16_f32 v54, v56, v57
	v_cvt_pk_bf16_f32 v55, v58, v59
	global_store_dwordx4 v34, v[52:55], s[6:7]
	s_add_u32 s6, s6, 0x1e0000
	s_addc_u32 s7, s7, 0
	s_waitcnt vmcnt(11)
	v_cvt_pk_bf16_f32 v60, v60, v61
	v_cvt_pk_bf16_f32 v61, v62, v63
	v_cvt_pk_bf16_f32 v62, v64, v65
	v_cvt_pk_bf16_f32 v63, v66, v67
	global_store_dwordx4 v34, v[60:63], s[6:7]
	s_add_u32 s6, s6, 0x1e0000
	s_addc_u32 s7, s7, 0
	s_waitcnt vmcnt(10)
	v_cvt_pk_bf16_f32 v68, v68, v69
	v_cvt_pk_bf16_f32 v69, v70, v71
	v_cvt_pk_bf16_f32 v70, v72, v73
	v_cvt_pk_bf16_f32 v71, v74, v75
	global_store_dwordx4 v34, v[68:71], s[6:7]
	s_add_u32 s6, s6, 0x1e0000
	s_addc_u32 s7, s7, 0
	s_waitcnt vmcnt(9)
	v_cvt_pk_bf16_f32 v76, v76, v77
	v_cvt_pk_bf16_f32 v77, v78, v79
	v_cvt_pk_bf16_f32 v78, v80, v81
	v_cvt_pk_bf16_f32 v79, v82, v83
	global_store_dwordx4 v34, v[76:79], s[6:7]
	s_add_u32 s6, s6, 0x1e0000
	s_addc_u32 s7, s7, 0
	s_waitcnt vmcnt(8)
	v_cvt_pk_bf16_f32 v84, v84, v85
	v_cvt_pk_bf16_f32 v85, v86, v87
	v_cvt_pk_bf16_f32 v86, v88, v89
	v_cvt_pk_bf16_f32 v87, v90, v91
	global_store_dwordx4 v34, v[84:87], s[6:7]
	s_add_u32 s6, s6, 0x1e0000
	s_addc_u32 s7, s7, 0
	s_waitcnt vmcnt(7)
	v_cvt_pk_bf16_f32 v92, v92, v93
	v_cvt_pk_bf16_f32 v93, v94, v95
	v_cvt_pk_bf16_f32 v94, v96, v97
	v_cvt_pk_bf16_f32 v95, v98, v99
	global_store_dwordx4 v34, v[92:95], s[6:7]
	s_add_u32 s6, s6, 0x1e0000
	s_addc_u32 s7, s7, 0
	s_cmp_lt_u32 s10, 0x400
	s_cbranch_scc0 .Lcvp_c
	v_cvt_pk_bf16_f32 v100, v100, v101
	v_cvt_pk_bf16_f32 v101, v102, v103
	v_cvt_pk_bf16_f32 v102, v104, v105
	v_cvt_pk_bf16_f32 v103, v106, v107
	global_store_dwordx4 v34, v[100:103], s[6:7]
